# P9: epilogues of the two wave halves staggered (align barrier only on the last tile, re-stagger barrier removed), so one half's epilogue overlaps the other half's MFMA phase
# speedup vs baseline: 1.0031x; 1.0031x over previous
; #define PG8_STAGE(bufoff, gbase, voff) do { _Pragma("unroll") for (int _i = 0; _i < 2; ++_i) \
;         __builtin_amdgcn_global_load_lds((const unsigned*)((const char*)(gbase) + (voff)[_i]), (LAS unsigned*)(lds + (bufoff) + ldsw + _i * 8192), 16, 0, 0); } while (0)
; #define PG8_LDA(dst, b, h) do { _Pragma("unroll") for (int m = 0; m < 4; ++m) _Pragma("unroll") for (int k = 0; k < 2; ++k) dst[m][k] = *(const LAS bf16x8*)(lds + PG8_SA(b, h) + aoff + m * 2048 + k * 1024); } while (0)
; #define PG8_LDB(dst, b, h) do { _Pragma("unroll") for (int n = 0; n < 2; ++n) _Pragma("unroll") for (int k = 0; k < 2; ++k) dst[n][k] = *(const LAS bf16x8*)(lds + PG8_SB(b, h) + boff + n * 2048 + k * 1024); } while (0)
; #define PG8_MMA(ai, bj, At, Bt) do { __builtin_amdgcn_s_setprio(1); _Pragma("unroll") for (int m = 0; m < 4; ++m) _Pragma("unroll") for (int n = 0; n < 2; ++n) _Pragma("unroll") for (int k = 0; k < 2; ++k) \
;         acc[ai][bj][m][n] = __builtin_amdgcn_mfma_f32_16x16x32_bf16(Bt[n][k], At[m][k], acc[ai][bj][m][n], 0, 0, 0); __builtin_amdgcn_s_setprio(0); } while (0)
; #define PG8_WAIT_V(n) asm volatile("s_waitcnt vmcnt(" #n ")" ::: "memory")
; #define PG8_WAIT_L(n) asm volatile("s_waitcnt lgkmcnt(" #n ")" ::: "memory")
; #define PG8_BAR __builtin_amdgcn_s_barrier()
; #define PG8_SCHED __builtin_amdgcn_sched_barrier(0)
; template <class GEO, class Epi>
; __device__ __forceinline__ void gemm_phase(LAS unsigned char* lds, const Gemm g, const StaticOrder& S, const Epi& E) {
;     ...
;             const bool last = (t == nt - 2);
;             const char* a1 = cA + (size_t)(t + 1) * kstep;
;             const char* a2 = last ? nA : cA + (size_t)(t + 2) * kstep; const char* b2 = last ? nB : cB + (size_t)(t + 2) * kstep;
;             const char* a3 = a2 + kstep; const char* b3 = b2 + kstep;
;             PG8_LDB(B0, 0, 0); PG8_LDB(B1, 0, 1); PG8_SCHED; PG8_LDA(At, 0, 0); PG8_STAGE(PG8_SA(1, 1), a1 + hstepA, voffA);
;             PG8_WAIT_V(8); PG8_WAIT_L(0); PG8_BAR; PG8_MMA(0, 0, At, B0); PG8_MMA(0, 1, At, B1); PG8_BAR; PG8_SCHED;
;             PG8_LDA(At, 0, 1); PG8_STAGE(PG8_SB(0, 0), b2, voffB); PG8_STAGE(PG8_SB(0, 1), b2 + hstepB, voffB); PG8_STAGE(PG8_SA(0, 0), a2, voffA);
.LBB0_1075:
	ds_read_b128 v[144:147], v151
	ds_read_b128 v[156:159], v151 offset:1024
	ds_read_b128 v[166:169], v151 offset:2048
	ds_read_b128 v[170:173], v151 offset:3072
	ds_read_b128 v[174:177], v152
	ds_read_b128 v[178:181], v152 offset:1024
	ds_read_b128 v[182:185], v152 offset:2048
	ds_read_b128 v[186:189], v152 offset:3072
	s_add_u32 s38, s22, 0xfffc0080
	s_addc_u32 s39, s23, -1
	s_cmp_eq_u32 s51, 12
	s_cselect_b32 s47, s21, s39
	s_cselect_b32 s46, s31, s38
	s_cselect_b32 s45, s14, s50
	s_cselect_b32 s44, s48, s49
	v_lshl_add_u64 v[160:161], s[22:23], 0, v[136:137]
	s_add_i32 m0, s1, 0xc000
	ds_read_b128 v[190:193], v153
	ds_read_b128 v[194:197], v153 offset:1024
	ds_read_b128 v[198:201], v153 offset:2048
	ds_read_b128 v[202:205], v153 offset:3072
	ds_read_b128 v[210:213], v153 offset:4096
	ds_read_b128 v[214:217], v153 offset:5120
	ds_read_b128 v[218:221], v153 offset:6144
	ds_read_b128 v[222:225], v153 offset:7168
	global_load_lds_dwordx4 v[160:161], off
	v_lshl_add_u64 v[160:161], s[22:23], 0, v[138:139]
	s_add_i32 m0, s1, 0xe000
	s_nop 0
	global_load_lds_dwordx4 v[160:161], off
	s_waitcnt vmcnt(8)
	s_waitcnt lgkmcnt(0)
	s_barrier
	s_waitcnt lgkmcnt(0)
	v_mfma_f32_16x16x32_bf16 v[124:127], v[144:147], v[190:193], v[124:127]
	v_mfma_f32_16x16x32_bf16 v[120:123], v[166:169], v[190:193], v[120:123]
	v_mfma_f32_16x16x32_bf16 v[108:111], v[144:147], v[198:201], v[108:111]
	v_mfma_f32_16x16x32_bf16 v[104:107], v[166:169], v[198:201], v[104:107]
	v_mfma_f32_16x16x32_bf16 v[92:95], v[144:147], v[210:213], v[92:95]
	v_mfma_f32_16x16x32_bf16 v[88:91], v[166:169], v[210:213], v[88:91]
	v_mfma_f32_16x16x32_bf16 v[76:79], v[144:147], v[218:221], v[76:79]
	v_mfma_f32_16x16x32_bf16 v[72:75], v[166:169], v[218:221], v[72:75]
	v_mfma_f32_16x16x32_bf16 v[124:127], v[156:159], v[194:197], v[124:127]
	v_mfma_f32_16x16x32_bf16 v[120:123], v[170:173], v[194:197], v[120:123]
	v_mfma_f32_16x16x32_bf16 v[108:111], v[156:159], v[202:205], v[108:111]
	v_mfma_f32_16x16x32_bf16 v[104:107], v[170:173], v[202:205], v[104:107]
	v_mfma_f32_16x16x32_bf16 v[92:95], v[156:159], v[214:217], v[92:95]
	v_mfma_f32_16x16x32_bf16 v[88:91], v[170:173], v[214:217], v[88:91]
	v_mfma_f32_16x16x32_bf16 v[76:79], v[156:159], v[222:225], v[76:79]
	v_mfma_f32_16x16x32_bf16 v[72:75], v[170:173], v[222:225], v[72:75]
	v_mfma_f32_16x16x32_bf16 v[116:119], v[174:177], v[190:193], v[116:119]
	v_mfma_f32_16x16x32_bf16 v[112:115], v[182:185], v[190:193], v[112:115]
	v_mfma_f32_16x16x32_bf16 v[100:103], v[174:177], v[198:201], v[100:103]
	v_mfma_f32_16x16x32_bf16 v[96:99], v[182:185], v[198:201], v[96:99]
	v_mfma_f32_16x16x32_bf16 v[84:87], v[174:177], v[210:213], v[84:87]
	v_mfma_f32_16x16x32_bf16 v[80:83], v[182:185], v[210:213], v[80:83]
	v_mfma_f32_16x16x32_bf16 v[68:71], v[174:177], v[218:221], v[68:71]
	v_mfma_f32_16x16x32_bf16 v[64:67], v[182:185], v[218:221], v[64:67]
	v_mfma_f32_16x16x32_bf16 v[116:119], v[178:181], v[194:197], v[116:119]
	v_mfma_f32_16x16x32_bf16 v[112:115], v[186:189], v[194:197], v[112:115]
	v_mfma_f32_16x16x32_bf16 v[100:103], v[178:181], v[202:205], v[100:103]
	v_mfma_f32_16x16x32_bf16 v[96:99], v[186:189], v[202:205], v[96:99]
	v_mfma_f32_16x16x32_bf16 v[84:87], v[178:181], v[214:217], v[84:87]
	v_mfma_f32_16x16x32_bf16 v[80:83], v[186:189], v[214:217], v[80:83]
	v_mfma_f32_16x16x32_bf16 v[68:71], v[178:181], v[222:225], v[68:71]
	v_mfma_f32_16x16x32_bf16 v[64:67], v[186:189], v[222:225], v[64:67]
	s_barrier
	s_add_i32 s38, s13, s0
	v_lshl_add_u64 v[160:161], s[44:45], 0, v[132:133]
	s_mov_b32 m0, s38
	ds_read_b128 v[190:193], v153 offset:16384
	ds_read_b128 v[194:197], v153 offset:17408
	ds_read_b128 v[198:201], v153 offset:18432
	ds_read_b128 v[202:205], v153 offset:19456
	ds_read_b128 v[210:213], v153 offset:20480
	ds_read_b128 v[214:217], v153 offset:21504
	ds_read_b128 v[218:221], v153 offset:22528
	ds_read_b128 v[222:225], v153 offset:23552
	global_load_lds_dwordx4 v[160:161], off
	s_add_i32 m0, s38, 0x2000
	s_add_u32 s38, s44, 0x40000
	v_lshl_add_u64 v[206:207], s[44:45], 0, v[128:129]
	s_addc_u32 s39, s45, 0
	s_add_i32 s52, s18, s0
	global_load_lds_dwordx4 v[206:207], off
	v_lshl_add_u64 v[226:227], s[38:39], 0, v[132:133]
	s_mov_b32 m0, s52
	v_lshl_add_u64 v[228:229], s[46:47], 0, v[130:131]
	global_load_lds_dwordx4 v[226:227], off
	v_lshl_add_u64 v[226:227], s[38:39], 0, v[128:129]
	s_add_i32 m0, s52, 0x2000
	s_nop 0
	global_load_lds_dwordx4 v[226:227], off
	v_lshl_add_u64 v[226:227], s[46:47], 0, v[134:135]
	s_mov_b32 m0, s1
	s_nop 0
	global_load_lds_dwordx4 v[226:227], off
	s_mov_b32 m0, s4
	s_nop 0
	global_load_lds_dwordx4 v[228:229], off
	s_waitcnt vmcnt(8)
	s_waitcnt lgkmcnt(0)
	s_barrier
; #define PG8_STAGE(bufoff, gbase, voff) do { _Pragma("unroll") for (int _i = 0; _i < 2; ++_i) \
;         __builtin_amdgcn_global_load_lds((const unsigned*)((const char*)(gbase) + (voff)[_i]), (LAS unsigned*)(lds + (bufoff) + ldsw + _i * 8192), 16, 0, 0); } while (0)
; #define PG8_LDA(dst, b, h) do { _Pragma("unroll") for (int m = 0; m < 4; ++m) _Pragma("unroll") for (int k = 0; k < 2; ++k) dst[m][k] = *(const LAS bf16x8*)(lds + PG8_SA(b, h) + aoff + m * 2048 + k * 1024); } while (0)
; #define PG8_LDB(dst, b, h) do { _Pragma("unroll") for (int n = 0; n < 2; ++n) _Pragma("unroll") for (int k = 0; k < 2; ++k) dst[n][k] = *(const LAS bf16x8*)(lds + PG8_SB(b, h) + boff + n * 2048 + k * 1024); } while (0)
; #define PG8_MMA(ai, bj, At, Bt) do { __builtin_amdgcn_s_setprio(1); _Pragma("unroll") for (int m = 0; m < 4; ++m) _Pragma("unroll") for (int n = 0; n < 2; ++n) _Pragma("unroll") for (int k = 0; k < 2; ++k) \
;         acc[ai][bj][m][n] = __builtin_amdgcn_mfma_f32_16x16x32_bf16(Bt[n][k], At[m][k], acc[ai][bj][m][n], 0, 0, 0); __builtin_amdgcn_s_setprio(0); } while (0)
; #define PG8_WAIT_V(n) asm volatile("s_waitcnt vmcnt(" #n ")" ::: "memory")
; #define PG8_WAIT_L(n) asm volatile("s_waitcnt lgkmcnt(" #n ")" ::: "memory")
; #define PG8_BAR __builtin_amdgcn_s_barrier()
; #define PG8_SCHED __builtin_amdgcn_sched_barrier(0)
; template <class GEO, class Epi>
; __device__ __forceinline__ void gemm_phase(LAS unsigned char* lds, const Gemm g, const StaticOrder& S, const Epi& E) {
;     ...
;             PG8_WAIT_V(8); PG8_WAIT_L(0); PG8_BAR; PG8_MMA(1, 0, At, B0); PG8_MMA(1, 1, At, B1); PG8_BAR; PG8_SCHED;
;             PG8_LDB(B0, 1, 0); PG8_LDB(B1, 1, 1); PG8_SCHED; PG8_LDA(At, 1, 0); PG8_STAGE(PG8_SA(0, 1), a2 + hstepA, voffA);
;             PG8_WAIT_V(8); PG8_WAIT_L(0); PG8_BAR; PG8_MMA(0, 0, At, B0); PG8_MMA(0, 1, At, B1); PG8_BAR; PG8_SCHED;
	s_waitcnt lgkmcnt(0)
	v_mfma_f32_16x16x32_bf16 v[60:63], v[144:147], v[190:193], v[60:63]
	v_mfma_f32_16x16x32_bf16 v[56:59], v[166:169], v[190:193], v[56:59]
	v_mfma_f32_16x16x32_bf16 v[44:47], v[144:147], v[198:201], v[44:47]
	v_mfma_f32_16x16x32_bf16 v[40:43], v[166:169], v[198:201], v[40:43]
	v_mfma_f32_16x16x32_bf16 v[28:31], v[144:147], v[210:213], v[28:31]
	v_mfma_f32_16x16x32_bf16 v[24:27], v[166:169], v[210:213], v[24:27]
	v_mfma_f32_16x16x32_bf16 v[12:15], v[144:147], v[218:221], v[12:15]
	v_mfma_f32_16x16x32_bf16 v[8:11], v[166:169], v[218:221], v[8:11]
	v_mfma_f32_16x16x32_bf16 v[60:63], v[156:159], v[194:197], v[60:63]
	v_mfma_f32_16x16x32_bf16 v[56:59], v[170:173], v[194:197], v[56:59]
	v_mfma_f32_16x16x32_bf16 v[44:47], v[156:159], v[202:205], v[44:47]
	v_mfma_f32_16x16x32_bf16 v[40:43], v[170:173], v[202:205], v[40:43]
	v_mfma_f32_16x16x32_bf16 v[28:31], v[156:159], v[214:217], v[28:31]
	v_mfma_f32_16x16x32_bf16 v[24:27], v[170:173], v[214:217], v[24:27]
	v_mfma_f32_16x16x32_bf16 v[12:15], v[156:159], v[222:225], v[12:15]
	v_mfma_f32_16x16x32_bf16 v[8:11], v[170:173], v[222:225], v[8:11]
	v_mfma_f32_16x16x32_bf16 v[52:55], v[174:177], v[190:193], v[52:55]
	v_mfma_f32_16x16x32_bf16 v[48:51], v[182:185], v[190:193], v[48:51]
	v_mfma_f32_16x16x32_bf16 v[36:39], v[174:177], v[198:201], v[36:39]
	v_mfma_f32_16x16x32_bf16 v[32:35], v[182:185], v[198:201], v[32:35]
	v_mfma_f32_16x16x32_bf16 v[20:23], v[174:177], v[210:213], v[20:23]
	v_mfma_f32_16x16x32_bf16 v[16:19], v[182:185], v[210:213], v[16:19]
	v_mfma_f32_16x16x32_bf16 v[4:7], v[174:177], v[218:221], v[4:7]
	v_mfma_f32_16x16x32_bf16 v[0:3], v[182:185], v[218:221], v[0:3]
	v_mfma_f32_16x16x32_bf16 v[52:55], v[178:181], v[194:197], v[52:55]
	v_mfma_f32_16x16x32_bf16 v[48:51], v[186:189], v[194:197], v[48:51]
	v_mfma_f32_16x16x32_bf16 v[36:39], v[178:181], v[202:205], v[36:39]
	v_mfma_f32_16x16x32_bf16 v[32:35], v[186:189], v[202:205], v[32:35]
	v_mfma_f32_16x16x32_bf16 v[20:23], v[178:181], v[214:217], v[20:23]
	v_mfma_f32_16x16x32_bf16 v[16:19], v[186:189], v[214:217], v[16:19]
	v_mfma_f32_16x16x32_bf16 v[4:7], v[178:181], v[222:225], v[4:7]
	v_mfma_f32_16x16x32_bf16 v[0:3], v[186:189], v[222:225], v[0:3]
	s_barrier
	s_add_i32 s52, 0, 0x18000
	v_add_u32_e32 v155, s52, v149
	s_add_i32 s53, 0, 0x1c000
	ds_read_b128 v[144:147], v155
	ds_read_b128 v[156:159], v155 offset:1024
	ds_read_b128 v[166:169], v155 offset:2048
	ds_read_b128 v[170:173], v155 offset:3072
	v_add_u32_e32 v155, s53, v149
	ds_read_b128 v[174:177], v155
	ds_read_b128 v[178:181], v155 offset:1024
	ds_read_b128 v[182:185], v155 offset:2048
	ds_read_b128 v[186:189], v155 offset:3072
	s_add_u32 s38, s46, 0x40000
	s_addc_u32 s39, s47, 0
	s_mov_b32 m0, s5
	v_lshl_add_u64 v[230:231], s[38:39], 0, v[134:135]
	ds_read_b128 v[190:193], v153 offset:32768
	ds_read_b128 v[194:197], v153 offset:33792
	ds_read_b128 v[198:201], v153 offset:34816
	ds_read_b128 v[202:205], v153 offset:35840
	ds_read_b128 v[210:213], v153 offset:36864
	ds_read_b128 v[214:217], v153 offset:37888
	ds_read_b128 v[218:221], v153 offset:38912
	ds_read_b128 v[222:225], v153 offset:39936
	global_load_lds_dwordx4 v[230:231], off
	v_lshl_add_u64 v[230:231], s[38:39], 0, v[130:131]
	s_mov_b32 m0, s6
	s_nop 0
	global_load_lds_dwordx4 v[230:231], off
	s_waitcnt vmcnt(8)
	s_waitcnt lgkmcnt(0)
	s_barrier
	s_waitcnt lgkmcnt(0)
	v_mfma_f32_16x16x32_bf16 v[124:127], v[144:147], v[190:193], v[124:127]
	v_mfma_f32_16x16x32_bf16 v[120:123], v[166:169], v[190:193], v[120:123]
	v_mfma_f32_16x16x32_bf16 v[108:111], v[144:147], v[198:201], v[108:111]
	v_mfma_f32_16x16x32_bf16 v[104:107], v[166:169], v[198:201], v[104:107]
	v_mfma_f32_16x16x32_bf16 v[92:95], v[144:147], v[210:213], v[92:95]
	v_mfma_f32_16x16x32_bf16 v[88:91], v[166:169], v[210:213], v[88:91]
	v_mfma_f32_16x16x32_bf16 v[76:79], v[144:147], v[218:221], v[76:79]
	v_mfma_f32_16x16x32_bf16 v[72:75], v[166:169], v[218:221], v[72:75]
	v_mfma_f32_16x16x32_bf16 v[124:127], v[156:159], v[194:197], v[124:127]
	v_mfma_f32_16x16x32_bf16 v[120:123], v[170:173], v[194:197], v[120:123]
	v_mfma_f32_16x16x32_bf16 v[108:111], v[156:159], v[202:205], v[108:111]
	v_mfma_f32_16x16x32_bf16 v[104:107], v[170:173], v[202:205], v[104:107]
	v_mfma_f32_16x16x32_bf16 v[92:95], v[156:159], v[214:217], v[92:95]
	v_mfma_f32_16x16x32_bf16 v[88:91], v[170:173], v[214:217], v[88:91]
	v_mfma_f32_16x16x32_bf16 v[76:79], v[156:159], v[222:225], v[76:79]
	v_mfma_f32_16x16x32_bf16 v[72:75], v[170:173], v[222:225], v[72:75]
	v_mfma_f32_16x16x32_bf16 v[116:119], v[174:177], v[190:193], v[116:119]
	v_mfma_f32_16x16x32_bf16 v[112:115], v[182:185], v[190:193], v[112:115]
	v_mfma_f32_16x16x32_bf16 v[100:103], v[174:177], v[198:201], v[100:103]
	v_mfma_f32_16x16x32_bf16 v[96:99], v[182:185], v[198:201], v[96:99]
	v_mfma_f32_16x16x32_bf16 v[84:87], v[174:177], v[210:213], v[84:87]
	v_mfma_f32_16x16x32_bf16 v[80:83], v[182:185], v[210:213], v[80:83]
	v_mfma_f32_16x16x32_bf16 v[68:71], v[174:177], v[218:221], v[68:71]
	v_mfma_f32_16x16x32_bf16 v[64:67], v[182:185], v[218:221], v[64:67]
	v_mfma_f32_16x16x32_bf16 v[116:119], v[178:181], v[194:197], v[116:119]
	v_mfma_f32_16x16x32_bf16 v[112:115], v[186:189], v[194:197], v[112:115]
	v_mfma_f32_16x16x32_bf16 v[100:103], v[178:181], v[202:205], v[100:103]
	v_mfma_f32_16x16x32_bf16 v[96:99], v[186:189], v[202:205], v[96:99]
	v_mfma_f32_16x16x32_bf16 v[84:87], v[178:181], v[214:217], v[84:87]
	v_mfma_f32_16x16x32_bf16 v[80:83], v[186:189], v[214:217], v[80:83]
	v_mfma_f32_16x16x32_bf16 v[68:71], v[178:181], v[222:225], v[68:71]
	v_mfma_f32_16x16x32_bf16 v[64:67], v[186:189], v[222:225], v[64:67]
	s_barrier
; DI unsigned pk2(float lo, float hi) { f32x2 v = {lo, hi}; bf16x2_t b = __builtin_convertvector(v, bf16x2_t); return __builtin_bit_cast(unsigned, b); }
; #define PG8_STAGE(bufoff, gbase, voff) do { _Pragma("unroll") for (int _i = 0; _i < 2; ++_i) \
;         __builtin_amdgcn_global_load_lds((const unsigned*)((const char*)(gbase) + (voff)[_i]), (LAS unsigned*)(lds + (bufoff) + ldsw + _i * 8192), 16, 0, 0); } while (0)
; #define PG8_LDA(dst, b, h) do { _Pragma("unroll") for (int m = 0; m < 4; ++m) _Pragma("unroll") for (int k = 0; k < 2; ++k) dst[m][k] = *(const LAS bf16x8*)(lds + PG8_SA(b, h) + aoff + m * 2048 + k * 1024); } while (0)
; #define PG8_WAIT_V(n) asm volatile("s_waitcnt vmcnt(" #n ")" ::: "memory")
; #define PG8_WAIT_L(n) asm volatile("s_waitcnt lgkmcnt(" #n ")" ::: "memory")
; #define PG8_BAR __builtin_amdgcn_s_barrier()
; #define PG8_SCHED __builtin_amdgcn_sched_barrier(0)
;     DI void operator()(Acc& acc, const Unit& u, int wr, int wc, int fr, int fq, LAS unsigned char*) const {
;     ...
;             for (int m = 0; m < 4; ++m) { const int row = u.pm * BM + ai * HALF + wr * 64 + m * 16 + fr; bf16_t* rowp = O + (size_t)row * ldc + col0;
;                 float rs = 1.0f; if (HAS_RS) { const f32x4 q4 = *(const f32x4*)(sumsq + (size_t)row * 4); rs = rsqrtf(((q4.x + q4.y) + (q4.z + q4.w)) * (1.0f / DM) + EPS); }
; #pragma unroll
;                 for (int bj = 0; bj < 2; ++bj) { f32x4 v0 = acc[ai][bj][m][0] * rs, v1 = acc[ai][bj][m][1] * rs;
;                     if (act) { v0 = __builtin_elementwise_max(v0, (f32x4){0.f, 0.f, 0.f, 0.f}); v1 = __builtin_elementwise_max(v1, (f32x4){0.f, 0.f, 0.f, 0.f}); v0 = v0 * v0; v1 = v1 * v1; }
;                     u32x4 w; w.x = pk2(v0.x, v0.y); w.y = pk2(v0.z, v0.w); w.z = pk2(v1.x, v1.y); w.w = pk2(v1.z, v1.w);
;                     if (act) __builtin_nontemporal_store(w, (u32x4*)(rowp + bj * HALF)); else *(u32x4*)(rowp + bj * HALF) = w; } }
; template <class GEO, class Epi>
; __device__ __forceinline__ void gemm_phase(LAS unsigned char* lds, const Gemm g, const StaticOrder& S, const Epi& E) {
;     ...
;             PG8_LDA(At, 1, 1); PG8_STAGE(PG8_SB(1, 0), b3, voffB); PG8_STAGE(PG8_SB(1, 1), b3 + hstepB, voffB); PG8_STAGE(PG8_SA(1, 0), a3, voffA);
;             PG8_WAIT_V(8); PG8_WAIT_L(0); PG8_BAR; PG8_MMA(1, 0, At, B0); PG8_MMA(1, 1, At, B1); PG8_BAR; PG8_SCHED;
;         }
;         if (wr == 0) PG8_BAR;
	s_add_i32 s38, s52, s0
	v_lshl_add_u64 v[160:161], v[160:161], 0, s[24:25]
	s_mov_b32 m0, s38
	ds_read_b128 v[190:193], v153 offset:49152
	ds_read_b128 v[194:197], v153 offset:50176
	ds_read_b128 v[198:201], v153 offset:51200
	ds_read_b128 v[202:205], v153 offset:52224
	ds_read_b128 v[210:213], v153 offset:53248
	ds_read_b128 v[214:217], v153 offset:54272
	ds_read_b128 v[218:221], v153 offset:55296
	ds_read_b128 v[222:225], v153 offset:56320
	global_load_lds_dwordx4 v[160:161], off
	s_add_i32 m0, s38, 0x2000
	s_add_u32 s38, s44, 0x40080
	v_lshl_add_u64 v[160:161], v[206:207], 0, s[24:25]
	s_addc_u32 s39, s45, 0
	s_add_i32 s44, s53, s0
	global_load_lds_dwordx4 v[160:161], off
	v_lshl_add_u64 v[160:161], s[38:39], 0, v[132:133]
	s_mov_b32 m0, s44
	s_nop 0
	global_load_lds_dwordx4 v[160:161], off
	v_lshl_add_u64 v[160:161], s[38:39], 0, v[128:129]
	s_add_i32 m0, s44, 0x2000
	s_nop 0
	global_load_lds_dwordx4 v[160:161], off
	v_lshl_add_u64 v[160:161], v[226:227], 0, s[24:25]
	s_mov_b32 m0, s7
	s_nop 0
	global_load_lds_dwordx4 v[160:161], off
	v_lshl_add_u64 v[160:161], v[228:229], 0, s[24:25]
	s_mov_b32 m0, s12
	s_nop 0
	global_load_lds_dwordx4 v[160:161], off
	s_waitcnt vmcnt(8)
	s_waitcnt lgkmcnt(0)
	s_barrier
	s_waitcnt lgkmcnt(0)
	v_mfma_f32_16x16x32_bf16 v[60:63], v[144:147], v[190:193], v[60:63]
	v_mfma_f32_16x16x32_bf16 v[56:59], v[166:169], v[190:193], v[56:59]
	v_mfma_f32_16x16x32_bf16 v[44:47], v[144:147], v[198:201], v[44:47]
	v_mfma_f32_16x16x32_bf16 v[40:43], v[166:169], v[198:201], v[40:43]
	v_mfma_f32_16x16x32_bf16 v[28:31], v[144:147], v[210:213], v[28:31]
	v_mfma_f32_16x16x32_bf16 v[24:27], v[166:169], v[210:213], v[24:27]
	v_mfma_f32_16x16x32_bf16 v[12:15], v[144:147], v[218:221], v[12:15]
	v_mfma_f32_16x16x32_bf16 v[8:11], v[166:169], v[218:221], v[8:11]
	v_mfma_f32_16x16x32_bf16 v[60:63], v[156:159], v[194:197], v[60:63]
	v_mfma_f32_16x16x32_bf16 v[56:59], v[170:173], v[194:197], v[56:59]
	v_mfma_f32_16x16x32_bf16 v[44:47], v[156:159], v[202:205], v[44:47]
	v_mfma_f32_16x16x32_bf16 v[40:43], v[170:173], v[202:205], v[40:43]
	v_mfma_f32_16x16x32_bf16 v[28:31], v[156:159], v[214:217], v[28:31]
	v_mfma_f32_16x16x32_bf16 v[24:27], v[170:173], v[214:217], v[24:27]
	v_mfma_f32_16x16x32_bf16 v[12:15], v[156:159], v[222:225], v[12:15]
	v_mfma_f32_16x16x32_bf16 v[8:11], v[170:173], v[222:225], v[8:11]
	v_mfma_f32_16x16x32_bf16 v[52:55], v[174:177], v[190:193], v[52:55]
	v_mfma_f32_16x16x32_bf16 v[48:51], v[182:185], v[190:193], v[48:51]
	v_mfma_f32_16x16x32_bf16 v[36:39], v[174:177], v[198:201], v[36:39]
	v_mfma_f32_16x16x32_bf16 v[32:35], v[182:185], v[198:201], v[32:35]
	v_mfma_f32_16x16x32_bf16 v[20:23], v[174:177], v[210:213], v[20:23]
	v_mfma_f32_16x16x32_bf16 v[16:19], v[182:185], v[210:213], v[16:19]
	v_mfma_f32_16x16x32_bf16 v[4:7], v[174:177], v[218:221], v[4:7]
	v_mfma_f32_16x16x32_bf16 v[0:3], v[182:185], v[218:221], v[0:3]
	v_mfma_f32_16x16x32_bf16 v[52:55], v[178:181], v[194:197], v[52:55]
	v_mfma_f32_16x16x32_bf16 v[48:51], v[186:189], v[194:197], v[48:51]
	v_mfma_f32_16x16x32_bf16 v[36:39], v[178:181], v[202:205], v[36:39]
	v_mfma_f32_16x16x32_bf16 v[32:35], v[186:189], v[202:205], v[32:35]
	v_mfma_f32_16x16x32_bf16 v[20:23], v[178:181], v[214:217], v[20:23]
	v_mfma_f32_16x16x32_bf16 v[16:19], v[186:189], v[214:217], v[16:19]
	v_mfma_f32_16x16x32_bf16 v[4:7], v[178:181], v[222:225], v[4:7]
	v_mfma_f32_16x16x32_bf16 v[0:3], v[186:189], v[222:225], v[0:3]
	s_barrier
	s_add_i32 s51, s51, 2
	s_add_u32 s22, s22, 0x100
	s_addc_u32 s23, s23, 0
	s_add_u32 s49, s49, 0x100
	s_addc_u32 s50, s50, 0
	s_cmp_gt_u32 s51, 13
	s_cbranch_scc0 .LBB0_1075
	v_lshl_add_u32 v144, s20, 8, v148
	v_lshl_or_b32 v146, s37, 8, v150
	v_ashrrev_i32_e32 v145, 31, v144
	v_ashrrev_i32_e32 v147, 31, v146
	v_lshl_add_u64 v[156:157], v[144:145], 4, s[8:9]
	global_load_dwordx4 v[166:169], v[156:157], off offset:2048
	global_load_dwordx4 v[170:173], v[156:157], off offset:2304
	global_load_dwordx4 v[174:177], v[156:157], off offset:2560
	global_load_dwordx4 v[178:181], v[156:157], off offset:2816
	s_andn2_b64 vcc, s[28:29], s[40:41]
	s_cbranch_vccz .LBB0_1078
	s_barrier
.LBB0_1078:
	v_lshlrev_b64 v[158:159], 13, v[144:145]
	v_lshl_add_u64 v[158:159], s[96:97], 0, v[158:159]
	v_lshlrev_b64 v[146:147], 1, v[146:147]
	v_lshl_add_u64 v[160:161], v[158:159], 0, v[146:147]
	s_mov_b64 s[20:21], -1
	s_mov_b32 s44, 0x20000
	s_mov_b32 s45, 0
	s_mov_b32 s46, 0x100000
	s_mov_b32 s47, 0
	v_lshl_add_u64 v[198:199], v[160:161], 0, s[46:47]
	v_add_f32_e32 v182, v232, v233
	v_add_f32_e32 v184, v236, v237
	v_add_f32_e32 v186, v240, v241
	v_add_f32_e32 v188, v244, v245
	v_add_f32_e32 v183, v234, v235
	v_add_f32_e32 v185, v238, v239
	v_add_f32_e32 v187, v242, v243
	v_add_f32_e32 v189, v246, v247
	v_add_f32_e32 v182, v182, v183
	v_add_f32_e32 v184, v184, v185
	v_add_f32_e32 v186, v186, v187
	v_add_f32_e32 v188, v188, v189
	v_fmamk_f32 v182, v182, 0x3a800000, v154
	v_fmamk_f32 v184, v184, 0x3a800000, v154
	v_fmamk_f32 v186, v186, 0x3a800000, v154
	v_fmamk_f32 v188, v188, 0x3a800000, v154
	v_rsq_f32_e32 v182, v182
	v_rsq_f32_e32 v184, v184
	v_rsq_f32_e32 v186, v186
	v_rsq_f32_e32 v188, v188
	v_pk_mul_f32 v[126:127], v[126:127], v[182:183] op_sel_hi:[1,0]
	v_pk_mul_f32 v[124:125], v[124:125], v[182:183] op_sel_hi:[1,0]
	v_pk_mul_f32 v[122:123], v[122:123], v[182:183] op_sel_hi:[1,0]
	v_pk_mul_f32 v[120:121], v[120:121], v[182:183] op_sel_hi:[1,0]
	v_max_f32_e32 v120, 0, v120
	v_max_f32_e32 v121, 0, v121
	v_max_f32_e32 v122, 0, v122
	v_max_f32_e32 v123, 0, v123
	v_max_f32_e32 v124, 0, v124
	v_max_f32_e32 v125, 0, v125
	v_max_f32_e32 v126, 0, v126
	v_max_f32_e32 v127, 0, v127
; DI unsigned pk2(float lo, float hi) { f32x2 v = {lo, hi}; bf16x2_t b = __builtin_convertvector(v, bf16x2_t); return __builtin_bit_cast(unsigned, b); }
;     DI void operator()(Acc& acc, const Unit& u, int wr, int wc, int fr, int fq, LAS unsigned char*) const {
;     ...
;             for (int m = 0; m < 4; ++m) { const int row = u.pm * BM + ai * HALF + wr * 64 + m * 16 + fr; bf16_t* rowp = O + (size_t)row * ldc + col0;
;                 float rs = 1.0f; if (HAS_RS) { const f32x4 q4 = *(const f32x4*)(sumsq + (size_t)row * 4); rs = rsqrtf(((q4.x + q4.y) + (q4.z + q4.w)) * (1.0f / DM) + EPS); }
; #pragma unroll
;                 for (int bj = 0; bj < 2; ++bj) { f32x4 v0 = acc[ai][bj][m][0] * rs, v1 = acc[ai][bj][m][1] * rs;
;                     if (act) { v0 = __builtin_elementwise_max(v0, (f32x4){0.f, 0.f, 0.f, 0.f}); v1 = __builtin_elementwise_max(v1, (f32x4){0.f, 0.f, 0.f, 0.f}); v0 = v0 * v0; v1 = v1 * v1; }
;                     u32x4 w; w.x = pk2(v0.x, v0.y); w.y = pk2(v0.z, v0.w); w.z = pk2(v1.x, v1.y); w.w = pk2(v1.z, v1.w);
;                     if (act) __builtin_nontemporal_store(w, (u32x4*)(rowp + bj * HALF)); else *(u32x4*)(rowp + bj * HALF) = w; } }
	v_pk_mul_f32 v[126:127], v[126:127], v[126:127]
	v_pk_mul_f32 v[124:125], v[124:125], v[124:125]
	v_pk_mul_f32 v[122:123], v[122:123], v[122:123]
	v_pk_mul_f32 v[120:121], v[120:121], v[120:121]
	v_cvt_pk_bf16_f32 v200, v124, v125
	v_cvt_pk_bf16_f32 v201, v126, v127
	v_cvt_pk_bf16_f32 v202, v120, v121
	v_cvt_pk_bf16_f32 v203, v122, v123
	global_store_dwordx4 v[160:161], v[200:203], off nt
	v_pk_mul_f32 v[118:119], v[118:119], v[182:183] op_sel_hi:[1,0]
	v_pk_mul_f32 v[116:117], v[116:117], v[182:183] op_sel_hi:[1,0]
	v_pk_mul_f32 v[114:115], v[114:115], v[182:183] op_sel_hi:[1,0]
	v_pk_mul_f32 v[112:113], v[112:113], v[182:183] op_sel_hi:[1,0]
	v_max_f32_e32 v112, 0, v112
	v_max_f32_e32 v113, 0, v113
	v_max_f32_e32 v114, 0, v114
	v_max_f32_e32 v115, 0, v115
	v_max_f32_e32 v116, 0, v116
	v_max_f32_e32 v117, 0, v117
	v_max_f32_e32 v118, 0, v118
	v_max_f32_e32 v119, 0, v119
	v_pk_mul_f32 v[118:119], v[118:119], v[118:119]
	v_pk_mul_f32 v[116:117], v[116:117], v[116:117]
	v_pk_mul_f32 v[114:115], v[114:115], v[114:115]
	v_pk_mul_f32 v[112:113], v[112:113], v[112:113]
	v_cvt_pk_bf16_f32 v204, v116, v117
	v_cvt_pk_bf16_f32 v205, v118, v119
	v_cvt_pk_bf16_f32 v206, v112, v113
	v_cvt_pk_bf16_f32 v207, v114, v115
	global_store_dwordx4 v[160:161], v[204:207], off offset:256 nt
	v_lshl_add_u64 v[158:159], v[160:161], 0, s[44:45]
	v_pk_mul_f32 v[110:111], v[110:111], v[184:185] op_sel_hi:[1,0]
	v_pk_mul_f32 v[108:109], v[108:109], v[184:185] op_sel_hi:[1,0]
	v_pk_mul_f32 v[106:107], v[106:107], v[184:185] op_sel_hi:[1,0]
	v_pk_mul_f32 v[104:105], v[104:105], v[184:185] op_sel_hi:[1,0]
	v_max_f32_e32 v104, 0, v104
	v_max_f32_e32 v105, 0, v105
	v_max_f32_e32 v106, 0, v106
	v_max_f32_e32 v107, 0, v107
	v_max_f32_e32 v108, 0, v108
	v_max_f32_e32 v109, 0, v109
	v_max_f32_e32 v110, 0, v110
	v_max_f32_e32 v111, 0, v111
	v_pk_mul_f32 v[110:111], v[110:111], v[110:111]
	v_pk_mul_f32 v[108:109], v[108:109], v[108:109]
	v_pk_mul_f32 v[106:107], v[106:107], v[106:107]
	v_pk_mul_f32 v[104:105], v[104:105], v[104:105]
	v_cvt_pk_bf16_f32 v210, v108, v109
	v_cvt_pk_bf16_f32 v211, v110, v111
	v_cvt_pk_bf16_f32 v212, v104, v105
	v_cvt_pk_bf16_f32 v213, v106, v107
	global_store_dwordx4 v[158:159], v[210:213], off nt
	v_pk_mul_f32 v[102:103], v[102:103], v[184:185] op_sel_hi:[1,0]
	v_pk_mul_f32 v[100:101], v[100:101], v[184:185] op_sel_hi:[1,0]
	v_pk_mul_f32 v[98:99], v[98:99], v[184:185] op_sel_hi:[1,0]
	v_pk_mul_f32 v[96:97], v[96:97], v[184:185] op_sel_hi:[1,0]
	v_max_f32_e32 v96, 0, v96
	v_max_f32_e32 v97, 0, v97
	v_max_f32_e32 v98, 0, v98
	v_max_f32_e32 v99, 0, v99
	v_max_f32_e32 v100, 0, v100
	v_max_f32_e32 v101, 0, v101
	v_max_f32_e32 v102, 0, v102
	v_max_f32_e32 v103, 0, v103
	v_pk_mul_f32 v[102:103], v[102:103], v[102:103]
	v_pk_mul_f32 v[100:101], v[100:101], v[100:101]
	v_pk_mul_f32 v[98:99], v[98:99], v[98:99]
	v_pk_mul_f32 v[96:97], v[96:97], v[96:97]
	v_cvt_pk_bf16_f32 v214, v100, v101
	v_cvt_pk_bf16_f32 v215, v102, v103
	v_cvt_pk_bf16_f32 v216, v96, v97
	v_cvt_pk_bf16_f32 v217, v98, v99
	global_store_dwordx4 v[158:159], v[214:217], off offset:256 nt
	v_lshl_add_u64 v[160:161], v[158:159], 0, s[44:45]
	v_pk_mul_f32 v[94:95], v[94:95], v[186:187] op_sel_hi:[1,0]
	v_pk_mul_f32 v[92:93], v[92:93], v[186:187] op_sel_hi:[1,0]
	v_pk_mul_f32 v[90:91], v[90:91], v[186:187] op_sel_hi:[1,0]
	v_pk_mul_f32 v[88:89], v[88:89], v[186:187] op_sel_hi:[1,0]
	v_max_f32_e32 v88, 0, v88
	v_max_f32_e32 v89, 0, v89
	v_max_f32_e32 v90, 0, v90
	v_max_f32_e32 v91, 0, v91
	v_max_f32_e32 v92, 0, v92
	v_max_f32_e32 v93, 0, v93
	v_max_f32_e32 v94, 0, v94
	v_max_f32_e32 v95, 0, v95
	v_pk_mul_f32 v[94:95], v[94:95], v[94:95]
	v_pk_mul_f32 v[92:93], v[92:93], v[92:93]
	v_pk_mul_f32 v[90:91], v[90:91], v[90:91]
	v_pk_mul_f32 v[88:89], v[88:89], v[88:89]
	v_cvt_pk_bf16_f32 v200, v92, v93
	v_cvt_pk_bf16_f32 v201, v94, v95
	v_cvt_pk_bf16_f32 v202, v88, v89
	v_cvt_pk_bf16_f32 v203, v90, v91
	global_store_dwordx4 v[160:161], v[200:203], off nt
	v_pk_mul_f32 v[86:87], v[86:87], v[186:187] op_sel_hi:[1,0]
	v_pk_mul_f32 v[84:85], v[84:85], v[186:187] op_sel_hi:[1,0]
	v_pk_mul_f32 v[82:83], v[82:83], v[186:187] op_sel_hi:[1,0]
	v_pk_mul_f32 v[80:81], v[80:81], v[186:187] op_sel_hi:[1,0]
	v_max_f32_e32 v80, 0, v80
	v_max_f32_e32 v81, 0, v81
	v_max_f32_e32 v82, 0, v82
	v_max_f32_e32 v83, 0, v83
	v_max_f32_e32 v84, 0, v84
	v_max_f32_e32 v85, 0, v85
	v_max_f32_e32 v86, 0, v86
	v_max_f32_e32 v87, 0, v87
	v_pk_mul_f32 v[86:87], v[86:87], v[86:87]
	v_pk_mul_f32 v[84:85], v[84:85], v[84:85]
	v_pk_mul_f32 v[82:83], v[82:83], v[82:83]
	v_pk_mul_f32 v[80:81], v[80:81], v[80:81]
	v_cvt_pk_bf16_f32 v204, v84, v85
	v_cvt_pk_bf16_f32 v205, v86, v87
	v_cvt_pk_bf16_f32 v206, v80, v81
	v_cvt_pk_bf16_f32 v207, v82, v83
	global_store_dwordx4 v[160:161], v[204:207], off offset:256 nt
	v_lshl_add_u64 v[158:159], v[160:161], 0, s[44:45]
	v_pk_mul_f32 v[78:79], v[78:79], v[188:189] op_sel_hi:[1,0]
	v_pk_mul_f32 v[76:77], v[76:77], v[188:189] op_sel_hi:[1,0]
	v_pk_mul_f32 v[74:75], v[74:75], v[188:189] op_sel_hi:[1,0]
	v_pk_mul_f32 v[72:73], v[72:73], v[188:189] op_sel_hi:[1,0]
	v_max_f32_e32 v72, 0, v72
	v_max_f32_e32 v73, 0, v73
	v_max_f32_e32 v74, 0, v74
	v_max_f32_e32 v75, 0, v75
	v_max_f32_e32 v76, 0, v76
	v_max_f32_e32 v77, 0, v77
	v_max_f32_e32 v78, 0, v78
	v_max_f32_e32 v79, 0, v79
	v_pk_mul_f32 v[78:79], v[78:79], v[78:79]
	v_pk_mul_f32 v[76:77], v[76:77], v[76:77]
	v_pk_mul_f32 v[74:75], v[74:75], v[74:75]
	v_pk_mul_f32 v[72:73], v[72:73], v[72:73]
	v_cvt_pk_bf16_f32 v210, v76, v77
	v_cvt_pk_bf16_f32 v211, v78, v79
	v_cvt_pk_bf16_f32 v212, v72, v73
	v_cvt_pk_bf16_f32 v213, v74, v75
	global_store_dwordx4 v[158:159], v[210:213], off nt
	v_pk_mul_f32 v[70:71], v[70:71], v[188:189] op_sel_hi:[1,0]
	v_pk_mul_f32 v[68:69], v[68:69], v[188:189] op_sel_hi:[1,0]
	v_pk_mul_f32 v[66:67], v[66:67], v[188:189] op_sel_hi:[1,0]
	v_pk_mul_f32 v[64:65], v[64:65], v[188:189] op_sel_hi:[1,0]
	v_max_f32_e32 v64, 0, v64
	v_max_f32_e32 v65, 0, v65
	v_max_f32_e32 v66, 0, v66
	v_max_f32_e32 v67, 0, v67
	v_max_f32_e32 v68, 0, v68
	v_max_f32_e32 v69, 0, v69
	v_max_f32_e32 v70, 0, v70
	v_max_f32_e32 v71, 0, v71
	v_pk_mul_f32 v[70:71], v[70:71], v[70:71]
	v_pk_mul_f32 v[68:69], v[68:69], v[68:69]
	v_pk_mul_f32 v[66:67], v[66:67], v[66:67]
	v_pk_mul_f32 v[64:65], v[64:65], v[64:65]
	v_cvt_pk_bf16_f32 v214, v68, v69
	v_cvt_pk_bf16_f32 v215, v70, v71
	v_cvt_pk_bf16_f32 v216, v64, v65
	v_cvt_pk_bf16_f32 v217, v66, v67
	global_store_dwordx4 v[158:159], v[214:217], off offset:256 nt
	s_waitcnt vmcnt(8)
; DI unsigned pk2(float lo, float hi) { f32x2 v = {lo, hi}; bf16x2_t b = __builtin_convertvector(v, bf16x2_t); return __builtin_bit_cast(unsigned, b); }
;     DI void operator()(Acc& acc, const Unit& u, int wr, int wc, int fr, int fq, LAS unsigned char*) const {
;     ...
;             for (int m = 0; m < 4; ++m) { const int row = u.pm * BM + ai * HALF + wr * 64 + m * 16 + fr; bf16_t* rowp = O + (size_t)row * ldc + col0;
;                 float rs = 1.0f; if (HAS_RS) { const f32x4 q4 = *(const f32x4*)(sumsq + (size_t)row * 4); rs = rsqrtf(((q4.x + q4.y) + (q4.z + q4.w)) * (1.0f / DM) + EPS); }
; #pragma unroll
;                 for (int bj = 0; bj < 2; ++bj) { f32x4 v0 = acc[ai][bj][m][0] * rs, v1 = acc[ai][bj][m][1] * rs;
;                     if (act) { v0 = __builtin_elementwise_max(v0, (f32x4){0.f, 0.f, 0.f, 0.f}); v1 = __builtin_elementwise_max(v1, (f32x4){0.f, 0.f, 0.f, 0.f}); v0 = v0 * v0; v1 = v1 * v1; }
;                     u32x4 w; w.x = pk2(v0.x, v0.y); w.y = pk2(v0.z, v0.w); w.z = pk2(v1.x, v1.y); w.w = pk2(v1.z, v1.w);
;                     if (act) __builtin_nontemporal_store(w, (u32x4*)(rowp + bj * HALF)); else *(u32x4*)(rowp + bj * HALF) = w; } }
	v_add_f32_e32 v190, v166, v167
	v_add_f32_e32 v192, v170, v171
	v_add_f32_e32 v194, v174, v175
	v_add_f32_e32 v196, v178, v179
	v_add_f32_e32 v191, v168, v169
	v_add_f32_e32 v193, v172, v173
	v_add_f32_e32 v195, v176, v177
	v_add_f32_e32 v197, v180, v181
	v_add_f32_e32 v190, v190, v191
	v_add_f32_e32 v192, v192, v193
	v_add_f32_e32 v194, v194, v195
	v_add_f32_e32 v196, v196, v197
	v_fmamk_f32 v190, v190, 0x3a800000, v154
	v_fmamk_f32 v192, v192, 0x3a800000, v154
	v_fmamk_f32 v194, v194, 0x3a800000, v154
	v_fmamk_f32 v196, v196, 0x3a800000, v154
	v_rsq_f32_e32 v190, v190
	v_rsq_f32_e32 v192, v192
	v_rsq_f32_e32 v194, v194
	v_rsq_f32_e32 v196, v196
	v_pk_mul_f32 v[62:63], v[62:63], v[190:191] op_sel_hi:[1,0]
	v_pk_mul_f32 v[60:61], v[60:61], v[190:191] op_sel_hi:[1,0]
	v_pk_mul_f32 v[58:59], v[58:59], v[190:191] op_sel_hi:[1,0]
	v_pk_mul_f32 v[56:57], v[56:57], v[190:191] op_sel_hi:[1,0]
	v_max_f32_e32 v56, 0, v56
	v_max_f32_e32 v57, 0, v57
	v_max_f32_e32 v58, 0, v58
	v_max_f32_e32 v59, 0, v59
	v_max_f32_e32 v60, 0, v60
	v_max_f32_e32 v61, 0, v61
	v_max_f32_e32 v62, 0, v62
	v_max_f32_e32 v63, 0, v63
	v_pk_mul_f32 v[62:63], v[62:63], v[62:63]
	v_pk_mul_f32 v[60:61], v[60:61], v[60:61]
	v_pk_mul_f32 v[58:59], v[58:59], v[58:59]
	v_pk_mul_f32 v[56:57], v[56:57], v[56:57]
	v_cvt_pk_bf16_f32 v200, v60, v61
	v_cvt_pk_bf16_f32 v201, v62, v63
	v_cvt_pk_bf16_f32 v202, v56, v57
	v_cvt_pk_bf16_f32 v203, v58, v59
	global_store_dwordx4 v[198:199], v[200:203], off nt
	v_pk_mul_f32 v[54:55], v[54:55], v[190:191] op_sel_hi:[1,0]
	v_pk_mul_f32 v[52:53], v[52:53], v[190:191] op_sel_hi:[1,0]
	v_pk_mul_f32 v[50:51], v[50:51], v[190:191] op_sel_hi:[1,0]
	v_pk_mul_f32 v[48:49], v[48:49], v[190:191] op_sel_hi:[1,0]
	v_max_f32_e32 v48, 0, v48
	v_max_f32_e32 v49, 0, v49
	v_max_f32_e32 v50, 0, v50
	v_max_f32_e32 v51, 0, v51
	v_max_f32_e32 v52, 0, v52
	v_max_f32_e32 v53, 0, v53
	v_max_f32_e32 v54, 0, v54
	v_max_f32_e32 v55, 0, v55
	v_pk_mul_f32 v[54:55], v[54:55], v[54:55]
	v_pk_mul_f32 v[52:53], v[52:53], v[52:53]
	v_pk_mul_f32 v[50:51], v[50:51], v[50:51]
	v_pk_mul_f32 v[48:49], v[48:49], v[48:49]
	v_cvt_pk_bf16_f32 v204, v52, v53
	v_cvt_pk_bf16_f32 v205, v54, v55
	v_cvt_pk_bf16_f32 v206, v48, v49
	v_cvt_pk_bf16_f32 v207, v50, v51
	global_store_dwordx4 v[198:199], v[204:207], off offset:256 nt
	v_lshl_add_u64 v[158:159], v[198:199], 0, s[44:45]
	v_pk_mul_f32 v[46:47], v[46:47], v[192:193] op_sel_hi:[1,0]
	v_pk_mul_f32 v[44:45], v[44:45], v[192:193] op_sel_hi:[1,0]
	v_pk_mul_f32 v[42:43], v[42:43], v[192:193] op_sel_hi:[1,0]
	v_pk_mul_f32 v[40:41], v[40:41], v[192:193] op_sel_hi:[1,0]
	v_max_f32_e32 v40, 0, v40
	v_max_f32_e32 v41, 0, v41
	v_max_f32_e32 v42, 0, v42
	v_max_f32_e32 v43, 0, v43
	v_max_f32_e32 v44, 0, v44
	v_max_f32_e32 v45, 0, v45
	v_max_f32_e32 v46, 0, v46
	v_max_f32_e32 v47, 0, v47
	v_pk_mul_f32 v[46:47], v[46:47], v[46:47]
	v_pk_mul_f32 v[44:45], v[44:45], v[44:45]
	v_pk_mul_f32 v[42:43], v[42:43], v[42:43]
	v_pk_mul_f32 v[40:41], v[40:41], v[40:41]
	v_cvt_pk_bf16_f32 v210, v44, v45
	v_cvt_pk_bf16_f32 v211, v46, v47
	v_cvt_pk_bf16_f32 v212, v40, v41
	v_cvt_pk_bf16_f32 v213, v42, v43
	global_store_dwordx4 v[158:159], v[210:213], off nt
	v_pk_mul_f32 v[38:39], v[38:39], v[192:193] op_sel_hi:[1,0]
	v_pk_mul_f32 v[36:37], v[36:37], v[192:193] op_sel_hi:[1,0]
	v_pk_mul_f32 v[34:35], v[34:35], v[192:193] op_sel_hi:[1,0]
	v_pk_mul_f32 v[32:33], v[32:33], v[192:193] op_sel_hi:[1,0]
	v_max_f32_e32 v32, 0, v32
	v_max_f32_e32 v33, 0, v33
	v_max_f32_e32 v34, 0, v34
	v_max_f32_e32 v35, 0, v35
	v_max_f32_e32 v36, 0, v36
	v_max_f32_e32 v37, 0, v37
	v_max_f32_e32 v38, 0, v38
	v_max_f32_e32 v39, 0, v39
	v_pk_mul_f32 v[38:39], v[38:39], v[38:39]
	v_pk_mul_f32 v[36:37], v[36:37], v[36:37]
; DI unsigned pk2(float lo, float hi) { f32x2 v = {lo, hi}; bf16x2_t b = __builtin_convertvector(v, bf16x2_t); return __builtin_bit_cast(unsigned, b); }
; #define PG8_BAR __builtin_amdgcn_s_barrier()
;     DI void operator()(Acc& acc, const Unit& u, int wr, int wc, int fr, int fq, LAS unsigned char*) const {
;     ...
;             for (int m = 0; m < 4; ++m) { const int row = u.pm * BM + ai * HALF + wr * 64 + m * 16 + fr; bf16_t* rowp = O + (size_t)row * ldc + col0;
;                 float rs = 1.0f; if (HAS_RS) { const f32x4 q4 = *(const f32x4*)(sumsq + (size_t)row * 4); rs = rsqrtf(((q4.x + q4.y) + (q4.z + q4.w)) * (1.0f / DM) + EPS); }
; #pragma unroll
;                 for (int bj = 0; bj < 2; ++bj) { f32x4 v0 = acc[ai][bj][m][0] * rs, v1 = acc[ai][bj][m][1] * rs;
;                     if (act) { v0 = __builtin_elementwise_max(v0, (f32x4){0.f, 0.f, 0.f, 0.f}); v1 = __builtin_elementwise_max(v1, (f32x4){0.f, 0.f, 0.f, 0.f}); v0 = v0 * v0; v1 = v1 * v1; }
;                     u32x4 w; w.x = pk2(v0.x, v0.y); w.y = pk2(v0.z, v0.w); w.z = pk2(v1.x, v1.y); w.w = pk2(v1.z, v1.w);
;                     if (act) __builtin_nontemporal_store(w, (u32x4*)(rowp + bj * HALF)); else *(u32x4*)(rowp + bj * HALF) = w; } }
; template <class GEO, class Epi>
; __device__ __forceinline__ void gemm_phase(LAS unsigned char* lds, const Gemm g, const StaticOrder& S, const Epi& E) {
;     ...
;         if (!has_next) break;
; #pragma unroll
;         for (int a = 0; a < 2; ++a)
; #pragma unroll
;             for (int b = 0; b < 2; ++b)
; #pragma unroll
;                 for (int m = 0; m < 4; ++m)
; #pragma unroll
;                     for (int n = 0; n < 2; ++n) acc[a][b][m][n] = (f32x4){0.f, 0.f, 0.f, 0.f};
;         cur = nxt; cA = nA; cB = nB; ++ui;
;         if (wr == 1) PG8_BAR;
	v_pk_mul_f32 v[34:35], v[34:35], v[34:35]
	v_pk_mul_f32 v[32:33], v[32:33], v[32:33]
	v_cvt_pk_bf16_f32 v214, v36, v37
	v_cvt_pk_bf16_f32 v215, v38, v39
	v_cvt_pk_bf16_f32 v216, v32, v33
	v_cvt_pk_bf16_f32 v217, v34, v35
	global_store_dwordx4 v[158:159], v[214:217], off offset:256 nt
	v_lshl_add_u64 v[160:161], v[158:159], 0, s[44:45]
	v_pk_mul_f32 v[30:31], v[30:31], v[194:195] op_sel_hi:[1,0]
	v_pk_mul_f32 v[28:29], v[28:29], v[194:195] op_sel_hi:[1,0]
	v_pk_mul_f32 v[26:27], v[26:27], v[194:195] op_sel_hi:[1,0]
	v_pk_mul_f32 v[24:25], v[24:25], v[194:195] op_sel_hi:[1,0]
	v_max_f32_e32 v24, 0, v24
	v_max_f32_e32 v25, 0, v25
	v_max_f32_e32 v26, 0, v26
	v_max_f32_e32 v27, 0, v27
	v_max_f32_e32 v28, 0, v28
	v_max_f32_e32 v29, 0, v29
	v_max_f32_e32 v30, 0, v30
	v_max_f32_e32 v31, 0, v31
	v_pk_mul_f32 v[30:31], v[30:31], v[30:31]
	v_pk_mul_f32 v[28:29], v[28:29], v[28:29]
	v_pk_mul_f32 v[26:27], v[26:27], v[26:27]
	v_pk_mul_f32 v[24:25], v[24:25], v[24:25]
	v_cvt_pk_bf16_f32 v200, v28, v29
	v_cvt_pk_bf16_f32 v201, v30, v31
	v_cvt_pk_bf16_f32 v202, v24, v25
	v_cvt_pk_bf16_f32 v203, v26, v27
	global_store_dwordx4 v[160:161], v[200:203], off nt
	v_pk_mul_f32 v[22:23], v[22:23], v[194:195] op_sel_hi:[1,0]
	v_pk_mul_f32 v[20:21], v[20:21], v[194:195] op_sel_hi:[1,0]
	v_pk_mul_f32 v[18:19], v[18:19], v[194:195] op_sel_hi:[1,0]
	v_pk_mul_f32 v[16:17], v[16:17], v[194:195] op_sel_hi:[1,0]
	v_max_f32_e32 v16, 0, v16
	v_max_f32_e32 v17, 0, v17
	v_max_f32_e32 v18, 0, v18
	v_max_f32_e32 v19, 0, v19
	v_max_f32_e32 v20, 0, v20
	v_max_f32_e32 v21, 0, v21
	v_max_f32_e32 v22, 0, v22
	v_max_f32_e32 v23, 0, v23
	v_pk_mul_f32 v[22:23], v[22:23], v[22:23]
	v_pk_mul_f32 v[20:21], v[20:21], v[20:21]
	v_pk_mul_f32 v[18:19], v[18:19], v[18:19]
	v_pk_mul_f32 v[16:17], v[16:17], v[16:17]
	v_cvt_pk_bf16_f32 v204, v20, v21
	v_cvt_pk_bf16_f32 v205, v22, v23
	v_cvt_pk_bf16_f32 v206, v16, v17
	v_cvt_pk_bf16_f32 v207, v18, v19
	global_store_dwordx4 v[160:161], v[204:207], off offset:256 nt
	v_lshl_add_u64 v[158:159], v[160:161], 0, s[44:45]
	v_pk_mul_f32 v[14:15], v[14:15], v[196:197] op_sel_hi:[1,0]
	v_pk_mul_f32 v[12:13], v[12:13], v[196:197] op_sel_hi:[1,0]
	v_pk_mul_f32 v[10:11], v[10:11], v[196:197] op_sel_hi:[1,0]
	v_pk_mul_f32 v[8:9], v[8:9], v[196:197] op_sel_hi:[1,0]
	v_max_f32_e32 v8, 0, v8
	v_max_f32_e32 v9, 0, v9
	v_max_f32_e32 v10, 0, v10
	v_max_f32_e32 v11, 0, v11
	v_max_f32_e32 v12, 0, v12
	v_max_f32_e32 v13, 0, v13
	v_max_f32_e32 v14, 0, v14
	v_max_f32_e32 v15, 0, v15
	v_pk_mul_f32 v[14:15], v[14:15], v[14:15]
	v_pk_mul_f32 v[12:13], v[12:13], v[12:13]
	v_pk_mul_f32 v[10:11], v[10:11], v[10:11]
	v_pk_mul_f32 v[8:9], v[8:9], v[8:9]
	v_cvt_pk_bf16_f32 v210, v12, v13
	v_cvt_pk_bf16_f32 v211, v14, v15
	v_cvt_pk_bf16_f32 v212, v8, v9
	v_cvt_pk_bf16_f32 v213, v10, v11
	global_store_dwordx4 v[158:159], v[210:213], off nt
	v_pk_mul_f32 v[6:7], v[6:7], v[196:197] op_sel_hi:[1,0]
	v_pk_mul_f32 v[4:5], v[4:5], v[196:197] op_sel_hi:[1,0]
	v_pk_mul_f32 v[2:3], v[2:3], v[196:197] op_sel_hi:[1,0]
	v_pk_mul_f32 v[0:1], v[0:1], v[196:197] op_sel_hi:[1,0]
	v_max_f32_e32 v0, 0, v0
	v_max_f32_e32 v1, 0, v1
	v_max_f32_e32 v2, 0, v2
	v_max_f32_e32 v3, 0, v3
	v_max_f32_e32 v4, 0, v4
	v_max_f32_e32 v5, 0, v5
	v_max_f32_e32 v6, 0, v6
	v_max_f32_e32 v7, 0, v7
	v_pk_mul_f32 v[6:7], v[6:7], v[6:7]
	v_pk_mul_f32 v[4:5], v[4:5], v[4:5]
	v_pk_mul_f32 v[2:3], v[2:3], v[2:3]
	v_pk_mul_f32 v[0:1], v[0:1], v[0:1]
	v_cvt_pk_bf16_f32 v214, v4, v5
	v_cvt_pk_bf16_f32 v215, v6, v7
	v_cvt_pk_bf16_f32 v216, v0, v1
	v_cvt_pk_bf16_f32 v217, v2, v3
	global_store_dwordx4 v[158:159], v[214:217], off offset:256 nt
	s_andn2_b64 vcc, exec, s[40:41]
	s_cbranch_vccnz .LBB0_1067
	s_branch .LBB0_1066
